# combination plus attention full-tile QK: the 8 K-fragment LDS reads issued together with counted waits
# speedup vs baseline: 1.0088x; 1.0010x over previous
.LBB0_291:
	s_or_b64 exec, exec, s[36:37]
	s_mul_hi_u32 s36, s54, 0xaaaaaaab
	s_lshr_b32 s36, s36, 2
	s_mul_i32 s36, s36, 0x18000
	v_subrev_u32_e32 v178, s36, v164
	v_subrev_u32_e32 v179, s36, v166
	v_subrev_u32_e32 v1, s36, v168
	v_subrev_u32_e32 v2, s36, v169
	v_subrev_u32_e32 v182, s36, v170
	v_subrev_u32_e32 v184, s36, v172
	v_subrev_u32_e32 v180, s36, v173
	v_subrev_u32_e32 v181, s36, v175
	v_subrev_u32_e32 v0, s36, v129
	v_subrev_u32_e32 v6, s36, v128
	v_subrev_u32_e32 v8, s36, v115
	v_subrev_u32_e32 v7, s36, v127
	s_barrier
	v_cmp_ge_i32_e32 vcc, s54, v123
	s_or_b64 s[36:37], s[48:49], vcc
	s_and_saveexec_b64 s[44:45], s[36:37]
	s_xor_b64 s[36:37], exec, s[44:45]
	s_cbranch_execz .LBB0_295
	v_add_u32_e32 v5, s53, v163
	v_add_u32_e32 v4, v5, v8
	v_add_u32_e32 v185, v5, v7
	v_add_u32_e32 v187, v5, v6
	v_add_u32_e32 v0, v5, v0
	ds_read_b128 v[8:11], v4
	ds_read_b128 v[12:15], v4 offset:4096
	ds_read_b128 v[96:99], v185
	ds_read_b128 v[188:191], v185 offset:4096
	ds_read_b128 v[192:195], v187
	ds_read_b128 v[196:199], v187 offset:4096
	ds_read_b128 v[226:229], v0
	ds_read_b128 v[230:233], v0 offset:4096
	s_waitcnt lgkmcnt(7)
	v_mfma_f32_32x32x16_f16 v[48:63], v[8:11], v[88:91], 0
	s_waitcnt lgkmcnt(6)
	v_mfma_f32_32x32x16_f16 v[64:79], v[12:15], v[88:91], 0
	s_waitcnt lgkmcnt(5)
	v_mfma_f32_32x32x16_f16 v[48:63], v[96:99], v[80:83], v[48:63]
	s_waitcnt lgkmcnt(4)
	v_mfma_f32_32x32x16_f16 v[64:79], v[188:191], v[80:83], v[64:79]
	s_waitcnt lgkmcnt(3)
	v_mfma_f32_32x32x16_f16 v[48:63], v[192:195], v[84:87], v[48:63]
	s_waitcnt lgkmcnt(2)
	v_mfma_f32_32x32x16_f16 v[64:79], v[196:199], v[84:87], v[64:79]
	s_waitcnt lgkmcnt(1)
	v_mfma_f32_32x32x16_f16 v[48:63], v[226:229], v[92:95], v[48:63]
	s_waitcnt lgkmcnt(0)
	v_mfma_f32_32x32x16_f16 v[64:79], v[230:233], v[92:95], v[64:79]
	s_nop 11
	v_max3_f32 v0, v48, s55, v64
	v_max3_f32 v0, v0, v49, v65
	v_max3_f32 v0, v0, v50, v66
	v_max3_f32 v0, v0, v51, v67
	v_max3_f32 v0, v0, v52, v68
	v_max3_f32 v0, v0, v53, v69
	v_max3_f32 v0, v0, v54, v70
	v_max3_f32 v0, v0, v55, v71
	v_max3_f32 v0, v0, v56, v72
	v_max3_f32 v0, v0, v57, v73
	v_max3_f32 v0, v0, v58, v74
	v_max3_f32 v0, v0, v59, v75
	v_max3_f32 v0, v0, v60, v76
	v_max3_f32 v0, v0, v61, v77
	v_max3_f32 v0, v0, v62, v78
	v_max3_f32 v0, v0, v63, v79
	v_mov_b32_e32 v4, v0
	s_nop 1
	v_permlane32_swap_b32_e32 v0, v4
	v_max3_f32 v4, v186, v0, v4
	v_sub_f32_e32 v0, v186, v4
	v_exp_f32_e32 v0, v0
	s_nop 0
	v_cmp_neq_f32_e32 vcc, 1.0, v0
	s_cbranch_vccz .LBB0_294
	v_mul_f32_e32 v30, v0, v30
	v_mul_f32_e32 v31, v0, v31
	v_mul_f32_e32 v28, v0, v28
	v_mul_f32_e32 v29, v0, v29
	v_mul_f32_e32 v26, v0, v26
	v_mul_f32_e32 v27, v0, v27
	v_mul_f32_e32 v24, v0, v24
	v_mul_f32_e32 v25, v0, v25
	v_mul_f32_e32 v22, v0, v22
	v_mul_f32_e32 v23, v0, v23
	v_mul_f32_e32 v20, v0, v20
	v_mul_f32_e32 v21, v0, v21
	v_mul_f32_e32 v18, v0, v18
	v_mul_f32_e32 v19, v0, v19
	v_mul_f32_e32 v16, v0, v16
	v_mul_f32_e32 v17, v0, v17
	v_mul_f32_e32 v46, v0, v46
	v_mul_f32_e32 v47, v0, v47
	v_mul_f32_e32 v44, v0, v44
	v_mul_f32_e32 v45, v0, v45
	v_mul_f32_e32 v42, v0, v42
	v_mul_f32_e32 v43, v0, v43
	v_mul_f32_e32 v40, v0, v40
	v_mul_f32_e32 v41, v0, v41
	v_mul_f32_e32 v38, v0, v38
	v_mul_f32_e32 v39, v0, v39
	v_mul_f32_e32 v36, v0, v36
	v_mul_f32_e32 v37, v0, v37
	v_mul_f32_e32 v34, v0, v34
	v_mul_f32_e32 v35, v0, v35
	v_mul_f32_e32 v32, v0, v32
	v_mul_f32_e32 v33, v0, v33
